# top-k rank ladder (64-way unrolled) replaced by a loop over valid blocks only
# speedup vs baseline: 1.0245x; 1.0051x over previous
; DI void cmp_item(const Params& p, int item, unsigned char* smem_) {
;     ...
; #pragma unroll 1
;   for (int q = 0; q < 16; ++q) {
;     const float mine = imps[wid * 1024 + q * 64 + lane]; int rank = 0;
; #pragma unroll
;     for (int i = 0; i < 64; ++i) { const float v = __uint_as_float(__builtin_amdgcn_readlane(__float_as_uint(mine), i)); rank += (v > mine || (v == mine && i < lane)) ? 1 : 0; }
;     const u64 m = __ballot(rank < 16);
;     if (lane == 0) sel[q] = m;
;   }
.LBB0_531:
	v_add_u32_e32 v3, s33, v2
	ds_read_b32 v3, v3
	v_readlane_b32 s36, v240, 2
	v_readlane_b32 s37, v240, 3
	s_waitcnt lgkmcnt(0)
	v_mov_b32_e32 v4, v3
	v_mov_b32_e32 v5, 0
	v_mov_b32_e32 v6, 0xcdee6b28
	v_cmp_lt_f32_e32 vcc, v6, v4
	s_nop 1
	s_bcnt1_i32_b64 s101, vcc
	s_add_i32 s101, s101, 1
	s_lshr_b32 s101, s101, 1
	s_mov_b64 s[98:99], -2
	s_mov_b32 s100, 0
.Lrk0:
	v_readlane_b32 s34, v4, s100
	s_add_i32 s100, s100, 1
	v_readlane_b32 s36, v4, s100
	s_add_i32 s100, s100, 1
	v_cmp_gt_f32_e32 vcc, s34, v4
	v_cmp_eq_f32_e64 s[30:31], s34, v4
	s_and_b64 s[30:31], s[30:31], s[98:99]
	s_or_b64 vcc, vcc, s[30:31]
	v_addc_co_u32_e32 v5, vcc, 0, v5, vcc
	s_lshl_b64 s[98:99], s[98:99], 1
	v_cmp_gt_f32_e32 vcc, s36, v4
	v_cmp_eq_f32_e64 s[30:31], s36, v4
	s_and_b64 s[30:31], s[30:31], s[98:99]
	s_or_b64 vcc, vcc, s[30:31]
	v_addc_co_u32_e32 v5, vcc, 0, v5, vcc
	s_lshl_b64 s[98:99], s[98:99], 1
	s_sub_i32 s101, s101, 1
	s_cmp_lg_u32 s101, 0
	s_cbranch_scc1 .Lrk0
	v_mov_b32_e32 v3, v5
	v_cmp_gt_u32_e32 vcc, 16, v3
	s_mov_b64 s[30:31], exec
	v_readlane_b32 s36, v240, 0
	v_readlane_b32 s37, v240, 1
	s_and_b64 s[36:37], s[30:31], s[36:37]
	s_mov_b64 exec, s[36:37]
	s_cbranch_execz .LBB0_530
	v_mov_b64_e32 v[4:5], vcc
	global_store_dwordx2 v[0:1], v[4:5], off
	s_branch .LBB0_530
